# role alternation phases +3/+5: 75% of the 8-unit blocks reordered
# speedup vs baseline: 1.0103x; 1.0103x over previous
; #define SUB(k, bit) (!(kargs()->li == 1 && (k) == lo) || ((kargs()->submask >> (bit)) & 1u))
; __global__ void __launch_bounds__(NWAVES * 64, 2) fwd(Args args_unused) {
;     ...
;         if (IN(pb + 3)) {
;             PH_PTRS PH_LAYER
;             if (SUB(pb + 3, 0)) {
.LBB0_1364:
	v_readlane_b32 s99, v254, 3
	s_nop 3
	s_lshr_b32 s99, s99, 3
	s_and_b32 s99, s99, 3
	s_mov_b32 s98, 2
	s_cmp_eq_u32 s99, 1
	s_cselect_b32 s98, 0, s98
	s_cmp_eq_u32 s99, 2
	s_cselect_b32 s98, 0, s98
	s_cmp_eq_u32 s99, 3
	s_cselect_b32 s98, 0, s98
